# in-projection epilogue stores write-through (sc1) and no L2 write-back at the XCD seam after an in-projection phase, on top of v11
# speedup vs baseline: 1.0158x; 1.0125x over previous
.LBB0_400:
	v_cvt_pk_bf16_f32 v128, v128, v129
	v_cvt_pk_bf16_f32 v129, v130, v131
	v_cvt_pk_bf16_f32 v130, v132, v133
	v_cvt_pk_bf16_f32 v131, v134, v135
	v_mov_b32_e32 v132, v178
	v_mov_b32_e32 v133, v178
	v_cndmask_b32_e64 v134, 0, 1, s[0:1]
	global_store_dwordx4 v[142:143], v[128:131], off sc1
	v_cmp_ne_u32_e64 s[42:43], 1, v134
	s_andn2_b64 vcc, exec, s[0:1]
	v_pk_mul_f32 v[128:129], v[118:119], v[132:133]
	v_pk_mul_f32 v[130:131], v[116:117], v[146:147]
	v_pk_mul_f32 v[132:133], v[114:115], v[132:133]
	v_pk_mul_f32 v[134:135], v[112:113], v[146:147]
	s_cbranch_vccnz .LBB0_402
	v_mul_f32_e32 v148, 0xbfb8aa3b, v130
	v_mul_f32_e32 v149, 0xbfb8aa3b, v131
	v_mul_f32_e32 v150, 0xbfb8aa3b, v128
	v_mul_f32_e32 v151, 0xbfb8aa3b, v129
	v_exp_f32_e32 v148, v148
	v_exp_f32_e32 v149, v149
	v_exp_f32_e32 v150, v150
	v_exp_f32_e32 v151, v151
	v_add_f32_e32 v148, 1.0, v148
	v_add_f32_e32 v149, 1.0, v149
	v_add_f32_e32 v150, 1.0, v150
	v_add_f32_e32 v151, 1.0, v151
	v_rcp_f32_e32 v148, v148
	v_rcp_f32_e32 v149, v149
	v_rcp_f32_e32 v150, v150
	v_rcp_f32_e32 v151, v151
	v_pk_mul_f32 v[130:131], v[130:131], v[148:149]
	v_mul_f32_e32 v148, 0xbfb8aa3b, v134
	v_pk_mul_f32 v[128:129], v[128:129], v[150:151]
	v_mul_f32_e32 v149, 0xbfb8aa3b, v135
	v_mul_f32_e32 v150, 0xbfb8aa3b, v132
	v_mul_f32_e32 v151, 0xbfb8aa3b, v133
	v_exp_f32_e32 v148, v148
	v_exp_f32_e32 v149, v149
	v_exp_f32_e32 v150, v150
	v_exp_f32_e32 v151, v151
	v_add_f32_e32 v148, 1.0, v148
	v_add_f32_e32 v149, 1.0, v149
	v_add_f32_e32 v150, 1.0, v150
	v_add_f32_e32 v151, 1.0, v151
	v_rcp_f32_e32 v148, v148
	v_rcp_f32_e32 v149, v149
	v_rcp_f32_e32 v150, v150
	v_rcp_f32_e32 v151, v151
	v_pk_mul_f32 v[134:135], v[134:135], v[148:149]
	v_pk_mul_f32 v[132:133], v[132:133], v[150:151]
.LBB0_402:
	v_cvt_pk_bf16_f32 v148, v130, v131
	v_cvt_pk_bf16_f32 v149, v128, v129
	v_cvt_pk_bf16_f32 v150, v134, v135
	v_cvt_pk_bf16_f32 v151, v132, v133
	global_store_dwordx4 v[142:143], v[148:151], off offset:256 sc1
	v_pk_mul_f32 v[130:131], v[100:101], v[178:179] op_sel:[0,1]
	v_pk_mul_f32 v[132:133], v[102:103], v[178:179] op_sel:[0,1]
	v_pk_mul_f32 v[134:135], v[96:97], v[178:179] op_sel:[0,1]
	s_and_b64 vcc, exec, s[42:43]
	v_pk_mul_f32 v[148:149], v[98:99], v[178:179] op_sel:[0,1]
	s_cbranch_vccnz .LBB0_404
	v_mul_f32_e32 v128, 0xbfb8aa3b, v130
	v_mul_f32_e32 v129, 0xbfb8aa3b, v131
	v_mul_f32_e32 v150, 0xbfb8aa3b, v132
	v_mul_f32_e32 v151, 0xbfb8aa3b, v133
	v_exp_f32_e32 v128, v128
	v_exp_f32_e32 v129, v129
	v_exp_f32_e32 v150, v150
	v_exp_f32_e32 v151, v151
	v_add_f32_e32 v128, 1.0, v128
	v_add_f32_e32 v129, 1.0, v129
	v_add_f32_e32 v150, 1.0, v150
	v_add_f32_e32 v151, 1.0, v151
	v_rcp_f32_e32 v128, v128
	v_rcp_f32_e32 v129, v129
	v_rcp_f32_e32 v150, v150
	v_rcp_f32_e32 v151, v151
	v_pk_mul_f32 v[130:131], v[130:131], v[128:129]
	v_mul_f32_e32 v128, 0xbfb8aa3b, v134
	v_pk_mul_f32 v[132:133], v[132:133], v[150:151]
	v_mul_f32_e32 v129, 0xbfb8aa3b, v135
	v_mul_f32_e32 v150, 0xbfb8aa3b, v148
	v_mul_f32_e32 v151, 0xbfb8aa3b, v149
	v_exp_f32_e32 v128, v128
	v_exp_f32_e32 v129, v129
	v_exp_f32_e32 v150, v150
	v_exp_f32_e32 v151, v151
	v_add_f32_e32 v128, 1.0, v128
	v_add_f32_e32 v129, 1.0, v129
	v_add_f32_e32 v150, 1.0, v150
	v_add_f32_e32 v151, 1.0, v151
	v_rcp_f32_e32 v128, v128
	v_rcp_f32_e32 v129, v129
	v_rcp_f32_e32 v150, v150
	v_rcp_f32_e32 v151, v151
	v_pk_mul_f32 v[134:135], v[134:135], v[128:129]
	v_pk_mul_f32 v[148:149], v[148:149], v[150:151]
.LBB0_404:
	v_mul_lo_u32 v151, s7, v176
	v_mul_lo_u32 v150, s6, v171
	v_mad_u64_u32 v[128:129], s[0:1], s6, v176, 0
	v_add3_u32 v129, v129, v150, v151
	v_mov_b32_e32 v180, v179
	v_mov_b32_e32 v181, v179
	v_lshl_add_u64 v[128:129], v[128:129], 1, v[138:139]
	v_cvt_pk_bf16_f32 v130, v130, v131
	v_cvt_pk_bf16_f32 v131, v132, v133
	v_cvt_pk_bf16_f32 v132, v134, v135
	v_cvt_pk_bf16_f32 v133, v148, v149
	v_mov_b32_e32 v134, v179
	v_mov_b32_e32 v135, v179
	global_store_dwordx4 v[128:129], v[130:133], off sc1
	s_and_b64 vcc, exec, s[42:43]
	v_pk_mul_f32 v[148:149], v[104:105], v[180:181]
	v_pk_mul_f32 v[130:131], v[110:111], v[134:135]
	v_pk_mul_f32 v[132:133], v[108:109], v[180:181]
	v_pk_mul_f32 v[134:135], v[106:107], v[134:135]
	s_cbranch_vccnz .LBB0_406
	v_mul_f32_e32 v151, 0xbfb8aa3b, v132
	v_exp_f32_e32 v151, v151
	s_nop 0
	v_add_f32_e32 v151, 1.0, v151
	v_rcp_f32_e32 v180, v151
	v_mul_f32_e32 v151, 0xbfb8aa3b, v133
	v_exp_f32_e32 v151, v151
	s_nop 0
	v_add_f32_e32 v151, 1.0, v151
	v_rcp_f32_e32 v181, v151
	v_mul_f32_e32 v151, 0xbfb8aa3b, v130
	v_exp_f32_e32 v151, v151
	v_pk_mul_f32 v[132:133], v[132:133], v[180:181]
	v_add_f32_e32 v151, 1.0, v151
	v_rcp_f32_e32 v202, v151
	v_mul_f32_e32 v151, 0xbfb8aa3b, v131
	v_exp_f32_e32 v151, v151
	s_nop 0
	v_add_f32_e32 v151, 1.0, v151
	v_rcp_f32_e32 v203, v151
	v_mul_f32_e32 v151, 0xbfb8aa3b, v148
	v_exp_f32_e32 v151, v151
	v_pk_mul_f32 v[130:131], v[130:131], v[202:203]
	v_add_f32_e32 v151, 1.0, v151
	v_rcp_f32_e32 v180, v151
	v_mul_f32_e32 v151, 0xbfb8aa3b, v149
	v_exp_f32_e32 v151, v151
	s_nop 0
	v_add_f32_e32 v151, 1.0, v151
	v_rcp_f32_e32 v181, v151
	v_mul_f32_e32 v151, 0xbfb8aa3b, v134
	v_exp_f32_e32 v151, v151
	v_pk_mul_f32 v[148:149], v[148:149], v[180:181]
	v_add_f32_e32 v151, 1.0, v151
	v_rcp_f32_e32 v202, v151
	v_mul_f32_e32 v151, 0xbfb8aa3b, v135
	v_exp_f32_e32 v151, v151
	s_nop 0
	v_add_f32_e32 v151, 1.0, v151
	v_rcp_f32_e32 v203, v151
	s_nop 0
	v_pk_mul_f32 v[134:135], v[134:135], v[202:203]
.LBB0_406:
	v_cvt_pk_bf16_f32 v202, v132, v133
	v_cvt_pk_bf16_f32 v203, v130, v131
	v_cvt_pk_bf16_f32 v204, v148, v149
	v_cvt_pk_bf16_f32 v205, v134, v135
	v_pk_mul_f32 v[130:131], v[84:85], v[144:145] op_sel_hi:[1,0]
	v_pk_mul_f32 v[132:133], v[86:87], v[144:145] op_sel_hi:[1,0]
	v_pk_mul_f32 v[134:135], v[80:81], v[144:145] op_sel_hi:[1,0]
	s_and_b64 vcc, exec, s[42:43]
	v_pk_mul_f32 v[148:149], v[82:83], v[144:145] op_sel_hi:[1,0]
	global_store_dwordx4 v[128:129], v[202:205], off offset:256 sc1
	s_cbranch_vccnz .LBB0_408
	v_mul_f32_e32 v151, 0xbfb8aa3b, v132
	v_exp_f32_e32 v151, v151
	v_mul_f32_e32 v128, 0xbfb8aa3b, v130
	v_mul_f32_e32 v129, 0xbfb8aa3b, v131
	v_exp_f32_e32 v128, v128
	v_add_f32_e32 v151, 1.0, v151
	v_rcp_f32_e32 v180, v151
	v_mul_f32_e32 v151, 0xbfb8aa3b, v133
	v_exp_f32_e32 v151, v151
	v_exp_f32_e32 v129, v129
	v_add_f32_e32 v128, 1.0, v128
	v_rcp_f32_e32 v128, v128
	v_add_f32_e32 v151, 1.0, v151
	v_rcp_f32_e32 v181, v151
	v_mul_f32_e32 v151, 0xbfb8aa3b, v148
	v_add_f32_e32 v129, 1.0, v129
	v_exp_f32_e32 v151, v151
	v_rcp_f32_e32 v129, v129
	v_pk_mul_f32 v[132:133], v[132:133], v[180:181]
	v_add_f32_e32 v151, 1.0, v151
	v_pk_mul_f32 v[130:131], v[130:131], v[128:129]
	v_mul_f32_e32 v128, 0xbfb8aa3b, v134
	v_mul_f32_e32 v129, 0xbfb8aa3b, v135
	v_rcp_f32_e32 v180, v151
	v_mul_f32_e32 v151, 0xbfb8aa3b, v149
	v_exp_f32_e32 v128, v128
	v_exp_f32_e32 v129, v129
	v_exp_f32_e32 v151, v151
	v_add_f32_e32 v128, 1.0, v128
	v_add_f32_e32 v129, 1.0, v129
	v_add_f32_e32 v151, 1.0, v151
	v_rcp_f32_e32 v128, v128
	v_rcp_f32_e32 v129, v129
	v_rcp_f32_e32 v181, v151
	v_pk_mul_f32 v[134:135], v[134:135], v[128:129]
	v_pk_mul_f32 v[148:149], v[148:149], v[180:181]
.LBB0_408:
	v_mul_lo_u32 v151, s7, v174
	v_mad_u64_u32 v[128:129], s[0:1], s6, v174, 0
	v_add3_u32 v129, v129, v150, v151
	v_mov_b32_e32 v180, v144
	v_mov_b32_e32 v181, v144
	v_lshl_add_u64 v[128:129], v[128:129], 1, v[138:139]
	v_cvt_pk_bf16_f32 v130, v130, v131
	v_cvt_pk_bf16_f32 v131, v132, v133
	v_cvt_pk_bf16_f32 v132, v134, v135
	v_cvt_pk_bf16_f32 v133, v148, v149
	v_mov_b32_e32 v134, v144
	v_mov_b32_e32 v135, v144
	global_store_dwordx4 v[128:129], v[130:133], off sc1
	s_and_b64 vcc, exec, s[42:43]
	v_pk_mul_f32 v[148:149], v[88:89], v[180:181]
	v_pk_mul_f32 v[130:131], v[94:95], v[134:135]
	v_pk_mul_f32 v[132:133], v[92:93], v[180:181]
	v_pk_mul_f32 v[134:135], v[90:91], v[134:135]
	s_cbranch_vccnz .LBB0_410
	v_mul_f32_e32 v151, 0xbfb8aa3b, v132
	v_exp_f32_e32 v151, v151
	s_nop 0
	v_add_f32_e32 v151, 1.0, v151
	v_rcp_f32_e32 v180, v151
	v_mul_f32_e32 v151, 0xbfb8aa3b, v133
	v_exp_f32_e32 v151, v151
	s_nop 0
	v_add_f32_e32 v151, 1.0, v151
	v_rcp_f32_e32 v181, v151
	v_mul_f32_e32 v151, 0xbfb8aa3b, v130
	v_exp_f32_e32 v151, v151
	v_pk_mul_f32 v[132:133], v[132:133], v[180:181]
	v_add_f32_e32 v151, 1.0, v151
	v_rcp_f32_e32 v202, v151
	v_mul_f32_e32 v151, 0xbfb8aa3b, v131
	v_exp_f32_e32 v151, v151
	s_nop 0
	v_add_f32_e32 v151, 1.0, v151
	v_rcp_f32_e32 v203, v151
	v_mul_f32_e32 v151, 0xbfb8aa3b, v148
	v_exp_f32_e32 v151, v151
	v_pk_mul_f32 v[130:131], v[130:131], v[202:203]
	v_add_f32_e32 v151, 1.0, v151
	v_rcp_f32_e32 v180, v151
	v_mul_f32_e32 v151, 0xbfb8aa3b, v149
	v_exp_f32_e32 v151, v151
	s_nop 0
	v_add_f32_e32 v151, 1.0, v151
	v_rcp_f32_e32 v181, v151
	v_mul_f32_e32 v151, 0xbfb8aa3b, v134
	v_exp_f32_e32 v151, v151
	v_pk_mul_f32 v[148:149], v[148:149], v[180:181]
	v_add_f32_e32 v151, 1.0, v151
	v_rcp_f32_e32 v202, v151
	v_mul_f32_e32 v151, 0xbfb8aa3b, v135
	v_exp_f32_e32 v151, v151
	s_nop 0
	v_add_f32_e32 v151, 1.0, v151
	v_rcp_f32_e32 v203, v151
	s_nop 0
	v_pk_mul_f32 v[134:135], v[134:135], v[202:203]
.LBB0_410:
	v_cvt_pk_bf16_f32 v202, v132, v133
	v_cvt_pk_bf16_f32 v203, v130, v131
	v_cvt_pk_bf16_f32 v204, v148, v149
	v_cvt_pk_bf16_f32 v205, v134, v135
	v_pk_mul_f32 v[130:131], v[68:69], v[144:145] op_sel:[0,1]
	v_pk_mul_f32 v[132:133], v[70:71], v[144:145] op_sel:[0,1]
	v_pk_mul_f32 v[134:135], v[64:65], v[144:145] op_sel:[0,1]
	s_and_b64 vcc, exec, s[42:43]
	v_pk_mul_f32 v[148:149], v[66:67], v[144:145] op_sel:[0,1]
	global_store_dwordx4 v[128:129], v[202:205], off offset:256 sc1
	s_cbranch_vccnz .LBB0_412
	v_mul_f32_e32 v151, 0xbfb8aa3b, v132
	v_exp_f32_e32 v151, v151
	v_mul_f32_e32 v128, 0xbfb8aa3b, v130
	v_mul_f32_e32 v129, 0xbfb8aa3b, v131
	v_exp_f32_e32 v128, v128
	v_add_f32_e32 v151, 1.0, v151
	v_rcp_f32_e32 v180, v151
	v_mul_f32_e32 v151, 0xbfb8aa3b, v133
	v_exp_f32_e32 v151, v151
	v_exp_f32_e32 v129, v129
	v_add_f32_e32 v128, 1.0, v128
	v_rcp_f32_e32 v128, v128
	v_add_f32_e32 v151, 1.0, v151
	v_rcp_f32_e32 v181, v151
	v_mul_f32_e32 v151, 0xbfb8aa3b, v148
	v_add_f32_e32 v129, 1.0, v129
	v_exp_f32_e32 v151, v151
	v_rcp_f32_e32 v129, v129
	v_pk_mul_f32 v[132:133], v[132:133], v[180:181]
	v_add_f32_e32 v151, 1.0, v151
	v_pk_mul_f32 v[130:131], v[130:131], v[128:129]
	v_mul_f32_e32 v128, 0xbfb8aa3b, v134
	v_mul_f32_e32 v129, 0xbfb8aa3b, v135
	v_rcp_f32_e32 v180, v151
	v_mul_f32_e32 v151, 0xbfb8aa3b, v149
	v_exp_f32_e32 v128, v128
	v_exp_f32_e32 v129, v129
	v_exp_f32_e32 v151, v151
	v_add_f32_e32 v128, 1.0, v128
	v_add_f32_e32 v129, 1.0, v129
	v_add_f32_e32 v151, 1.0, v151
	v_rcp_f32_e32 v128, v128
	v_rcp_f32_e32 v129, v129
	v_rcp_f32_e32 v181, v151
	v_pk_mul_f32 v[134:135], v[134:135], v[128:129]
	v_pk_mul_f32 v[148:149], v[148:149], v[180:181]
.LBB0_412:
	v_mul_lo_u32 v151, s7, v172
	v_mad_u64_u32 v[128:129], s[0:1], s6, v172, 0
	v_add3_u32 v129, v129, v150, v151
	v_mov_b32_e32 v180, v145
	v_mov_b32_e32 v181, v145
	v_lshl_add_u64 v[128:129], v[128:129], 1, v[138:139]
	v_cvt_pk_bf16_f32 v130, v130, v131
	v_cvt_pk_bf16_f32 v131, v132, v133
	v_cvt_pk_bf16_f32 v132, v134, v135
	v_cvt_pk_bf16_f32 v133, v148, v149
	v_mov_b32_e32 v134, v145
	v_mov_b32_e32 v135, v145
	global_store_dwordx4 v[128:129], v[130:133], off sc1
	s_and_b64 vcc, exec, s[42:43]
	v_pk_mul_f32 v[148:149], v[72:73], v[180:181]
	v_pk_mul_f32 v[130:131], v[78:79], v[134:135]
	v_pk_mul_f32 v[132:133], v[76:77], v[180:181]
	v_pk_mul_f32 v[134:135], v[74:75], v[134:135]
	s_cbranch_vccnz .LBB0_414
	v_mul_f32_e32 v173, 0xbfb8aa3b, v130
	v_exp_f32_e32 v173, v173
	v_mul_f32_e32 v150, 0xbfb8aa3b, v132
	v_mul_f32_e32 v151, 0xbfb8aa3b, v133
	v_exp_f32_e32 v150, v150
	v_add_f32_e32 v173, 1.0, v173
	v_rcp_f32_e32 v180, v173
	v_mul_f32_e32 v173, 0xbfb8aa3b, v131
	v_exp_f32_e32 v173, v173
	v_exp_f32_e32 v151, v151
	v_add_f32_e32 v150, 1.0, v150
	v_rcp_f32_e32 v150, v150
	v_add_f32_e32 v173, 1.0, v173
	v_rcp_f32_e32 v181, v173
	v_mul_f32_e32 v173, 0xbfb8aa3b, v134
	v_add_f32_e32 v151, 1.0, v151
	v_exp_f32_e32 v173, v173
	v_rcp_f32_e32 v151, v151
	v_pk_mul_f32 v[130:131], v[130:131], v[180:181]
	v_add_f32_e32 v173, 1.0, v173
	v_pk_mul_f32 v[132:133], v[132:133], v[150:151]
	v_mul_f32_e32 v150, 0xbfb8aa3b, v148
	v_mul_f32_e32 v151, 0xbfb8aa3b, v149
	v_rcp_f32_e32 v180, v173
	v_mul_f32_e32 v173, 0xbfb8aa3b, v135
	v_exp_f32_e32 v150, v150
	v_exp_f32_e32 v151, v151
	v_exp_f32_e32 v173, v173
	v_add_f32_e32 v150, 1.0, v150
	v_add_f32_e32 v151, 1.0, v151
	v_add_f32_e32 v173, 1.0, v173
	v_rcp_f32_e32 v150, v150
	v_rcp_f32_e32 v151, v151
	v_rcp_f32_e32 v181, v173
	v_pk_mul_f32 v[148:149], v[148:149], v[150:151]
	v_pk_mul_f32 v[134:135], v[134:135], v[180:181]
.LBB0_414:
	v_cvt_pk_bf16_f32 v202, v132, v133
	v_cvt_pk_bf16_f32 v203, v130, v131
	v_cvt_pk_bf16_f32 v204, v148, v149
	v_cvt_pk_bf16_f32 v205, v134, v135
	v_pk_mul_f32 v[130:131], v[52:53], v[140:141] op_sel_hi:[1,0]
	v_pk_mul_f32 v[132:133], v[54:55], v[140:141] op_sel_hi:[1,0]
	v_pk_mul_f32 v[134:135], v[48:49], v[140:141] op_sel_hi:[1,0]
	s_and_b64 vcc, exec, s[42:43]
	v_pk_mul_f32 v[148:149], v[50:51], v[140:141] op_sel_hi:[1,0]
	global_store_dwordx4 v[128:129], v[202:205], off offset:256 sc1
	s_cbranch_vccnz .LBB0_416
	v_mul_f32_e32 v128, 0xbfb8aa3b, v130
	v_mul_f32_e32 v129, 0xbfb8aa3b, v131
	v_mul_f32_e32 v150, 0xbfb8aa3b, v132
	v_mul_f32_e32 v151, 0xbfb8aa3b, v133
	v_exp_f32_e32 v128, v128
	v_exp_f32_e32 v129, v129
	v_exp_f32_e32 v150, v150
	v_exp_f32_e32 v151, v151
	v_add_f32_e32 v128, 1.0, v128
	v_add_f32_e32 v129, 1.0, v129
	v_add_f32_e32 v150, 1.0, v150
	v_add_f32_e32 v151, 1.0, v151
	v_rcp_f32_e32 v128, v128
	v_rcp_f32_e32 v129, v129
	v_rcp_f32_e32 v150, v150
	v_rcp_f32_e32 v151, v151
	v_pk_mul_f32 v[130:131], v[130:131], v[128:129]
	v_mul_f32_e32 v128, 0xbfb8aa3b, v134
	v_pk_mul_f32 v[132:133], v[132:133], v[150:151]
	v_mul_f32_e32 v129, 0xbfb8aa3b, v135
	v_mul_f32_e32 v150, 0xbfb8aa3b, v148
	v_mul_f32_e32 v151, 0xbfb8aa3b, v149
	v_exp_f32_e32 v128, v128
	v_exp_f32_e32 v129, v129
	v_exp_f32_e32 v150, v150
	v_exp_f32_e32 v151, v151
	v_add_f32_e32 v128, 1.0, v128
	v_add_f32_e32 v129, 1.0, v129
	v_add_f32_e32 v150, 1.0, v150
	v_add_f32_e32 v151, 1.0, v151
	v_rcp_f32_e32 v128, v128
	v_rcp_f32_e32 v129, v129
	v_rcp_f32_e32 v150, v150
	v_rcp_f32_e32 v151, v151
	v_pk_mul_f32 v[134:135], v[134:135], v[128:129]
	v_pk_mul_f32 v[148:149], v[148:149], v[150:151]
.LBB0_416:
	v_add_u32_e32 v128, 0x80, v170
	v_ashrrev_i32_e32 v129, 31, v128
	v_mul_lo_u32 v173, s6, v129
	v_mul_lo_u32 v175, s7, v128
	v_mad_u64_u32 v[128:129], s[0:1], s6, v128, 0
	v_add3_u32 v129, v129, v173, v175
	v_mov_b32_e32 v150, v140
	v_mov_b32_e32 v151, v140
	v_lshl_add_u64 v[128:129], v[128:129], 1, v[138:139]
	v_cvt_pk_bf16_f32 v130, v130, v131
	v_cvt_pk_bf16_f32 v131, v132, v133
	v_cvt_pk_bf16_f32 v132, v134, v135
	v_cvt_pk_bf16_f32 v133, v148, v149
	v_mov_b32_e32 v134, v140
	v_mov_b32_e32 v135, v140
	global_store_dwordx4 v[128:129], v[130:133], off sc1
	s_and_b64 vcc, exec, s[42:43]
	v_pk_mul_f32 v[148:149], v[56:57], v[150:151]
	v_pk_mul_f32 v[130:131], v[62:63], v[134:135]
	v_pk_mul_f32 v[132:133], v[60:61], v[150:151]
	v_pk_mul_f32 v[134:135], v[58:59], v[134:135]
	s_cbranch_vccnz .LBB0_418
	v_mul_f32_e32 v173, 0xbfb8aa3b, v130
	v_exp_f32_e32 v173, v173
	v_mul_f32_e32 v150, 0xbfb8aa3b, v132
	v_mul_f32_e32 v151, 0xbfb8aa3b, v133
	v_exp_f32_e32 v150, v150
	v_add_f32_e32 v173, 1.0, v173
	v_rcp_f32_e32 v180, v173
	v_mul_f32_e32 v173, 0xbfb8aa3b, v131
	v_exp_f32_e32 v173, v173
	v_exp_f32_e32 v151, v151
	v_add_f32_e32 v150, 1.0, v150
	v_rcp_f32_e32 v150, v150
	v_add_f32_e32 v173, 1.0, v173
	v_rcp_f32_e32 v181, v173
	v_mul_f32_e32 v173, 0xbfb8aa3b, v134
	v_add_f32_e32 v151, 1.0, v151
	v_exp_f32_e32 v173, v173
	v_rcp_f32_e32 v151, v151
	v_pk_mul_f32 v[130:131], v[130:131], v[180:181]
	v_add_f32_e32 v173, 1.0, v173
	v_pk_mul_f32 v[132:133], v[132:133], v[150:151]
	v_mul_f32_e32 v150, 0xbfb8aa3b, v148
	v_mul_f32_e32 v151, 0xbfb8aa3b, v149
	v_rcp_f32_e32 v180, v173
	v_mul_f32_e32 v173, 0xbfb8aa3b, v135
	v_exp_f32_e32 v150, v150
	v_exp_f32_e32 v151, v151
	v_exp_f32_e32 v173, v173
	v_add_f32_e32 v150, 1.0, v150
	v_add_f32_e32 v151, 1.0, v151
	v_add_f32_e32 v173, 1.0, v173
	v_rcp_f32_e32 v150, v150
	v_rcp_f32_e32 v151, v151
	v_rcp_f32_e32 v181, v173
	v_pk_mul_f32 v[148:149], v[148:149], v[150:151]
	v_pk_mul_f32 v[134:135], v[134:135], v[180:181]
.LBB0_418:
	v_cvt_pk_bf16_f32 v202, v132, v133
	v_cvt_pk_bf16_f32 v203, v130, v131
	v_cvt_pk_bf16_f32 v204, v148, v149
	v_cvt_pk_bf16_f32 v205, v134, v135
	v_pk_mul_f32 v[130:131], v[36:37], v[140:141] op_sel:[0,1]
	v_pk_mul_f32 v[132:133], v[38:39], v[140:141] op_sel:[0,1]
	v_pk_mul_f32 v[134:135], v[32:33], v[140:141] op_sel:[0,1]
	s_and_b64 vcc, exec, s[42:43]
	v_pk_mul_f32 v[148:149], v[34:35], v[140:141] op_sel:[0,1]
	global_store_dwordx4 v[128:129], v[202:205], off offset:256 sc1
	s_cbranch_vccnz .LBB0_420
	v_mul_f32_e32 v128, 0xbfb8aa3b, v130
	v_mul_f32_e32 v129, 0xbfb8aa3b, v131
	v_mul_f32_e32 v150, 0xbfb8aa3b, v132
	v_mul_f32_e32 v151, 0xbfb8aa3b, v133
	v_exp_f32_e32 v128, v128
	v_exp_f32_e32 v129, v129
	v_exp_f32_e32 v150, v150
	v_exp_f32_e32 v151, v151
	v_add_f32_e32 v128, 1.0, v128
	v_add_f32_e32 v129, 1.0, v129
	v_add_f32_e32 v150, 1.0, v150
	v_add_f32_e32 v151, 1.0, v151
	v_rcp_f32_e32 v128, v128
	v_rcp_f32_e32 v129, v129
	v_rcp_f32_e32 v150, v150
	v_rcp_f32_e32 v151, v151
	v_pk_mul_f32 v[130:131], v[130:131], v[128:129]
	v_mul_f32_e32 v128, 0xbfb8aa3b, v134
	v_pk_mul_f32 v[132:133], v[132:133], v[150:151]
	v_mul_f32_e32 v129, 0xbfb8aa3b, v135
	v_mul_f32_e32 v150, 0xbfb8aa3b, v148
	v_mul_f32_e32 v151, 0xbfb8aa3b, v149
	v_exp_f32_e32 v128, v128
	v_exp_f32_e32 v129, v129
	v_exp_f32_e32 v150, v150
	v_exp_f32_e32 v151, v151
	v_add_f32_e32 v128, 1.0, v128
	v_add_f32_e32 v129, 1.0, v129
	v_add_f32_e32 v150, 1.0, v150
	v_add_f32_e32 v151, 1.0, v151
	v_rcp_f32_e32 v128, v128
	v_rcp_f32_e32 v129, v129
	v_rcp_f32_e32 v150, v150
	v_rcp_f32_e32 v151, v151
	v_pk_mul_f32 v[134:135], v[134:135], v[128:129]
	v_pk_mul_f32 v[148:149], v[148:149], v[150:151]
.LBB0_420:
	v_add_u32_e32 v128, 0x90, v170
	v_ashrrev_i32_e32 v129, 31, v128
	v_mul_lo_u32 v173, s6, v129
	v_mul_lo_u32 v175, s7, v128
	v_mad_u64_u32 v[128:129], s[0:1], s6, v128, 0
	v_add3_u32 v129, v129, v173, v175
	v_mov_b32_e32 v150, v141
	v_mov_b32_e32 v151, v141
	v_lshl_add_u64 v[128:129], v[128:129], 1, v[138:139]
	v_cvt_pk_bf16_f32 v130, v130, v131
	v_cvt_pk_bf16_f32 v131, v132, v133
	v_cvt_pk_bf16_f32 v132, v134, v135
	v_cvt_pk_bf16_f32 v133, v148, v149
	v_mov_b32_e32 v134, v141
	v_mov_b32_e32 v135, v141
	global_store_dwordx4 v[128:129], v[130:133], off sc1
	s_and_b64 vcc, exec, s[42:43]
	v_pk_mul_f32 v[148:149], v[40:41], v[150:151]
	v_pk_mul_f32 v[130:131], v[46:47], v[134:135]
	v_pk_mul_f32 v[132:133], v[44:45], v[150:151]
	v_pk_mul_f32 v[134:135], v[42:43], v[134:135]
	s_cbranch_vccnz .LBB0_422
	v_mul_f32_e32 v173, 0xbfb8aa3b, v130
	v_exp_f32_e32 v173, v173
	v_mul_f32_e32 v150, 0xbfb8aa3b, v132
	v_mul_f32_e32 v151, 0xbfb8aa3b, v133
	v_exp_f32_e32 v150, v150
	v_add_f32_e32 v173, 1.0, v173
	v_rcp_f32_e32 v180, v173
	v_mul_f32_e32 v173, 0xbfb8aa3b, v131
	v_exp_f32_e32 v173, v173
	v_exp_f32_e32 v151, v151
	v_add_f32_e32 v150, 1.0, v150
	v_rcp_f32_e32 v150, v150
	v_add_f32_e32 v173, 1.0, v173
	v_rcp_f32_e32 v181, v173
	v_mul_f32_e32 v173, 0xbfb8aa3b, v134
	v_add_f32_e32 v151, 1.0, v151
	v_exp_f32_e32 v173, v173
	v_rcp_f32_e32 v151, v151
	v_pk_mul_f32 v[130:131], v[130:131], v[180:181]
	v_add_f32_e32 v173, 1.0, v173
	v_pk_mul_f32 v[132:133], v[132:133], v[150:151]
	v_mul_f32_e32 v150, 0xbfb8aa3b, v148
	v_mul_f32_e32 v151, 0xbfb8aa3b, v149
	v_rcp_f32_e32 v180, v173
	v_mul_f32_e32 v173, 0xbfb8aa3b, v135
	v_exp_f32_e32 v150, v150
	v_exp_f32_e32 v151, v151
	v_exp_f32_e32 v173, v173
	v_add_f32_e32 v150, 1.0, v150
	v_add_f32_e32 v151, 1.0, v151
	v_add_f32_e32 v173, 1.0, v173
	v_rcp_f32_e32 v150, v150
	v_rcp_f32_e32 v151, v151
	v_rcp_f32_e32 v181, v173
	v_pk_mul_f32 v[148:149], v[148:149], v[150:151]
	v_pk_mul_f32 v[134:135], v[134:135], v[180:181]
.LBB0_422:
	v_cvt_pk_bf16_f32 v202, v132, v133
	v_cvt_pk_bf16_f32 v203, v130, v131
	v_cvt_pk_bf16_f32 v204, v148, v149
	v_cvt_pk_bf16_f32 v205, v134, v135
	v_pk_mul_f32 v[130:131], v[20:21], v[136:137] op_sel_hi:[1,0]
	v_pk_mul_f32 v[132:133], v[22:23], v[136:137] op_sel_hi:[1,0]
	v_pk_mul_f32 v[134:135], v[16:17], v[136:137] op_sel_hi:[1,0]
	s_and_b64 vcc, exec, s[42:43]
	v_pk_mul_f32 v[148:149], v[18:19], v[136:137] op_sel_hi:[1,0]
	global_store_dwordx4 v[128:129], v[202:205], off offset:256 sc1
	s_cbranch_vccnz .LBB0_424
	v_mul_f32_e32 v128, 0xbfb8aa3b, v130
	v_mul_f32_e32 v129, 0xbfb8aa3b, v131
	v_mul_f32_e32 v150, 0xbfb8aa3b, v132
	v_mul_f32_e32 v151, 0xbfb8aa3b, v133
	v_exp_f32_e32 v128, v128
	v_exp_f32_e32 v129, v129
	v_exp_f32_e32 v150, v150
	v_exp_f32_e32 v151, v151
	v_add_f32_e32 v128, 1.0, v128
	v_add_f32_e32 v129, 1.0, v129
	v_add_f32_e32 v150, 1.0, v150
	v_add_f32_e32 v151, 1.0, v151
	v_rcp_f32_e32 v128, v128
	v_rcp_f32_e32 v129, v129
	v_rcp_f32_e32 v150, v150
	v_rcp_f32_e32 v151, v151
	v_pk_mul_f32 v[130:131], v[130:131], v[128:129]
	v_mul_f32_e32 v128, 0xbfb8aa3b, v134
	v_pk_mul_f32 v[132:133], v[132:133], v[150:151]
	v_mul_f32_e32 v129, 0xbfb8aa3b, v135
	v_mul_f32_e32 v150, 0xbfb8aa3b, v148
	v_mul_f32_e32 v151, 0xbfb8aa3b, v149
	v_exp_f32_e32 v128, v128
	v_exp_f32_e32 v129, v129
	v_exp_f32_e32 v150, v150
	v_exp_f32_e32 v151, v151
	v_add_f32_e32 v128, 1.0, v128
	v_add_f32_e32 v129, 1.0, v129
	v_add_f32_e32 v150, 1.0, v150
	v_add_f32_e32 v151, 1.0, v151
	v_rcp_f32_e32 v128, v128
	v_rcp_f32_e32 v129, v129
	v_rcp_f32_e32 v150, v150
	v_rcp_f32_e32 v151, v151
	v_pk_mul_f32 v[134:135], v[134:135], v[128:129]
	v_pk_mul_f32 v[148:149], v[148:149], v[150:151]
.LBB0_424:
	v_add_u32_e32 v128, 0xa0, v170
	v_ashrrev_i32_e32 v129, 31, v128
	v_mul_lo_u32 v173, s6, v129
	v_mul_lo_u32 v175, s7, v128
	v_mad_u64_u32 v[128:129], s[0:1], s6, v128, 0
	v_add3_u32 v129, v129, v173, v175
	v_mov_b32_e32 v150, v136
	v_mov_b32_e32 v151, v136
	v_lshl_add_u64 v[128:129], v[128:129], 1, v[138:139]
	v_cvt_pk_bf16_f32 v130, v130, v131
	v_cvt_pk_bf16_f32 v131, v132, v133
	v_cvt_pk_bf16_f32 v132, v134, v135
	v_cvt_pk_bf16_f32 v133, v148, v149
	v_mov_b32_e32 v134, v136
	v_mov_b32_e32 v135, v136
	global_store_dwordx4 v[128:129], v[130:133], off sc1
	s_and_b64 vcc, exec, s[42:43]
	v_pk_mul_f32 v[148:149], v[24:25], v[150:151]
	v_pk_mul_f32 v[130:131], v[30:31], v[134:135]
	v_pk_mul_f32 v[132:133], v[28:29], v[150:151]
	v_pk_mul_f32 v[134:135], v[26:27], v[134:135]
	s_cbranch_vccnz .LBB0_426
	v_mul_f32_e32 v173, 0xbfb8aa3b, v130
	v_exp_f32_e32 v173, v173
	v_mul_f32_e32 v150, 0xbfb8aa3b, v132
	v_mul_f32_e32 v151, 0xbfb8aa3b, v133
	v_exp_f32_e32 v150, v150
	v_add_f32_e32 v173, 1.0, v173
	v_rcp_f32_e32 v180, v173
	v_mul_f32_e32 v173, 0xbfb8aa3b, v131
	v_exp_f32_e32 v173, v173
	v_exp_f32_e32 v151, v151
	v_add_f32_e32 v150, 1.0, v150
	v_rcp_f32_e32 v150, v150
	v_add_f32_e32 v173, 1.0, v173
	v_rcp_f32_e32 v181, v173
	v_mul_f32_e32 v173, 0xbfb8aa3b, v134
	v_add_f32_e32 v151, 1.0, v151
	v_exp_f32_e32 v173, v173
	v_rcp_f32_e32 v151, v151
	v_pk_mul_f32 v[130:131], v[130:131], v[180:181]
	v_add_f32_e32 v173, 1.0, v173
	v_pk_mul_f32 v[132:133], v[132:133], v[150:151]
	v_mul_f32_e32 v150, 0xbfb8aa3b, v148
	v_mul_f32_e32 v151, 0xbfb8aa3b, v149
	v_rcp_f32_e32 v180, v173
	v_mul_f32_e32 v173, 0xbfb8aa3b, v135
	v_exp_f32_e32 v150, v150
	v_exp_f32_e32 v151, v151
	v_exp_f32_e32 v173, v173
	v_add_f32_e32 v150, 1.0, v150
	v_add_f32_e32 v151, 1.0, v151
	v_add_f32_e32 v173, 1.0, v173
	v_rcp_f32_e32 v150, v150
	v_rcp_f32_e32 v151, v151
	v_rcp_f32_e32 v181, v173
	v_pk_mul_f32 v[148:149], v[148:149], v[150:151]
	v_pk_mul_f32 v[134:135], v[134:135], v[180:181]
.LBB0_426:
	v_cvt_pk_bf16_f32 v202, v132, v133
	v_cvt_pk_bf16_f32 v203, v130, v131
	v_cvt_pk_bf16_f32 v204, v148, v149
	v_cvt_pk_bf16_f32 v205, v134, v135
	v_pk_mul_f32 v[130:131], v[4:5], v[136:137] op_sel:[0,1]
	v_pk_mul_f32 v[132:133], v[6:7], v[136:137] op_sel:[0,1]
	v_pk_mul_f32 v[134:135], v[0:1], v[136:137] op_sel:[0,1]
	s_and_b64 vcc, exec, s[42:43]
	v_pk_mul_f32 v[148:149], v[2:3], v[136:137] op_sel:[0,1]
	global_store_dwordx4 v[128:129], v[202:205], off offset:256 sc1
	s_cbranch_vccnz .LBB0_428
	v_mul_f32_e32 v128, 0xbfb8aa3b, v130
	v_mul_f32_e32 v129, 0xbfb8aa3b, v131
	v_mul_f32_e32 v150, 0xbfb8aa3b, v132
	v_mul_f32_e32 v151, 0xbfb8aa3b, v133
	v_exp_f32_e32 v128, v128
	v_exp_f32_e32 v129, v129
	v_exp_f32_e32 v150, v150
	v_exp_f32_e32 v151, v151
	v_add_f32_e32 v128, 1.0, v128
	v_add_f32_e32 v129, 1.0, v129
	v_add_f32_e32 v150, 1.0, v150
	v_add_f32_e32 v151, 1.0, v151
	v_rcp_f32_e32 v128, v128
	v_rcp_f32_e32 v129, v129
	v_rcp_f32_e32 v150, v150
	v_rcp_f32_e32 v151, v151
	v_pk_mul_f32 v[130:131], v[130:131], v[128:129]
	v_mul_f32_e32 v128, 0xbfb8aa3b, v134
	v_pk_mul_f32 v[132:133], v[132:133], v[150:151]
	v_mul_f32_e32 v129, 0xbfb8aa3b, v135
	v_mul_f32_e32 v150, 0xbfb8aa3b, v148
	v_mul_f32_e32 v151, 0xbfb8aa3b, v149
	v_exp_f32_e32 v128, v128
	v_exp_f32_e32 v129, v129
	v_exp_f32_e32 v150, v150
	v_exp_f32_e32 v151, v151
	v_add_f32_e32 v128, 1.0, v128
	v_add_f32_e32 v129, 1.0, v129
	v_add_f32_e32 v150, 1.0, v150
	v_add_f32_e32 v151, 1.0, v151
	v_rcp_f32_e32 v128, v128
	v_rcp_f32_e32 v129, v129
	v_rcp_f32_e32 v150, v150
	v_rcp_f32_e32 v151, v151
	v_pk_mul_f32 v[134:135], v[134:135], v[128:129]
	v_pk_mul_f32 v[148:149], v[148:149], v[150:151]
.LBB0_428:
	v_add_u32_e32 v128, 0xb0, v170
	v_ashrrev_i32_e32 v129, 31, v128
	v_mul_lo_u32 v173, s6, v129
	v_mul_lo_u32 v175, s7, v128
	v_mad_u64_u32 v[128:129], s[0:1], s6, v128, 0
	v_add3_u32 v129, v129, v173, v175
	v_mov_b32_e32 v150, v137
	v_mov_b32_e32 v151, v137
	v_lshl_add_u64 v[128:129], v[128:129], 1, v[138:139]
	v_cvt_pk_bf16_f32 v130, v130, v131
	v_cvt_pk_bf16_f32 v131, v132, v133
	v_cvt_pk_bf16_f32 v132, v134, v135
	v_cvt_pk_bf16_f32 v133, v148, v149
	v_mov_b32_e32 v134, v137
	v_mov_b32_e32 v135, v137
	global_store_dwordx4 v[128:129], v[130:133], off sc1
	s_and_b64 vcc, exec, s[42:43]
	v_pk_mul_f32 v[148:149], v[8:9], v[150:151]
	v_pk_mul_f32 v[130:131], v[14:15], v[134:135]
	v_pk_mul_f32 v[132:133], v[12:13], v[150:151]
	v_pk_mul_f32 v[134:135], v[10:11], v[134:135]
	s_cbranch_vccnz .LBB0_430
	v_mul_f32_e32 v173, 0xbfb8aa3b, v130
	v_exp_f32_e32 v173, v173
	v_mul_f32_e32 v150, 0xbfb8aa3b, v132
	v_mul_f32_e32 v151, 0xbfb8aa3b, v133
	v_exp_f32_e32 v150, v150
	v_add_f32_e32 v173, 1.0, v173
	v_rcp_f32_e32 v180, v173
	v_mul_f32_e32 v173, 0xbfb8aa3b, v131
	v_exp_f32_e32 v173, v173
	v_exp_f32_e32 v151, v151
	v_add_f32_e32 v150, 1.0, v150
	v_rcp_f32_e32 v150, v150
	v_add_f32_e32 v173, 1.0, v173
	v_rcp_f32_e32 v181, v173
	v_mul_f32_e32 v173, 0xbfb8aa3b, v134
	v_add_f32_e32 v151, 1.0, v151
	v_exp_f32_e32 v173, v173
	v_rcp_f32_e32 v151, v151
	v_pk_mul_f32 v[130:131], v[130:131], v[180:181]
	v_add_f32_e32 v173, 1.0, v173
	v_pk_mul_f32 v[132:133], v[132:133], v[150:151]
	v_mul_f32_e32 v150, 0xbfb8aa3b, v148
	v_mul_f32_e32 v151, 0xbfb8aa3b, v149
	v_rcp_f32_e32 v180, v173
	v_mul_f32_e32 v173, 0xbfb8aa3b, v135
	v_exp_f32_e32 v150, v150
	v_exp_f32_e32 v151, v151
	v_exp_f32_e32 v173, v173
	v_add_f32_e32 v150, 1.0, v150
	v_add_f32_e32 v151, 1.0, v151
	v_add_f32_e32 v173, 1.0, v173
	v_rcp_f32_e32 v150, v150
	v_rcp_f32_e32 v151, v151
	v_rcp_f32_e32 v181, v173
	v_pk_mul_f32 v[148:149], v[148:149], v[150:151]
	v_pk_mul_f32 v[134:135], v[134:135], v[180:181]
.LBB0_430:
	v_cvt_pk_bf16_f32 v202, v132, v133
	v_cvt_pk_bf16_f32 v203, v130, v131
	v_cvt_pk_bf16_f32 v204, v148, v149
	v_cvt_pk_bf16_f32 v205, v134, v135
	global_store_dwordx4 v[128:129], v[202:205], off offset:256 sc1

.LBB0_435:
	v_pk_mul_f32 v[118:119], v[122:123], v[118:119]
	v_pk_mul_f32 v[116:117], v[120:121], v[116:117]
	v_pk_mul_f32 v[120:121], v[126:127], v[114:115]
	v_pk_mul_f32 v[114:115], v[124:125], v[112:113]
	v_cvt_pk_bf16_f32 v112, v116, v117
	v_cvt_pk_bf16_f32 v113, v118, v119
	v_cvt_pk_bf16_f32 v114, v114, v115
	v_cvt_pk_bf16_f32 v115, v120, v121
	global_store_dwordx4 v[142:143], v[112:115], off sc1
	v_pk_mul_f32 v[108:109], v[108:109], v[178:179] op_sel:[0,1]
	v_pk_mul_f32 v[110:111], v[110:111], v[178:179] op_sel:[0,1]
	v_cndmask_b32_e64 v112, 0, 1, s[0:1]
	v_pk_mul_f32 v[104:105], v[104:105], v[178:179] op_sel:[0,1]
	v_cmp_ne_u32_e64 s[42:43], 1, v112
	s_andn2_b64 vcc, exec, s[0:1]
	v_pk_mul_f32 v[106:107], v[106:107], v[178:179] op_sel:[0,1]
	s_cbranch_vccnz .LBB0_437
	v_mul_f32_e32 v112, 0xbfb8aa3b, v108
	v_mul_f32_e32 v113, 0xbfb8aa3b, v109
	v_mul_f32_e32 v114, 0xbfb8aa3b, v110
	v_mul_f32_e32 v115, 0xbfb8aa3b, v111
	v_exp_f32_e32 v112, v112
	v_exp_f32_e32 v113, v113
	v_exp_f32_e32 v114, v114
	v_exp_f32_e32 v115, v115
	v_add_f32_e32 v112, 1.0, v112
	v_add_f32_e32 v113, 1.0, v113
	v_add_f32_e32 v114, 1.0, v114
	v_add_f32_e32 v115, 1.0, v115
	v_rcp_f32_e32 v112, v112
	v_rcp_f32_e32 v113, v113
	v_rcp_f32_e32 v114, v114
	v_rcp_f32_e32 v115, v115
	v_pk_mul_f32 v[108:109], v[108:109], v[112:113]
	v_mul_f32_e32 v112, 0xbfb8aa3b, v104
	v_pk_mul_f32 v[110:111], v[110:111], v[114:115]
	v_mul_f32_e32 v113, 0xbfb8aa3b, v105
	v_mul_f32_e32 v114, 0xbfb8aa3b, v106
	v_mul_f32_e32 v115, 0xbfb8aa3b, v107
	v_exp_f32_e32 v112, v112
	v_exp_f32_e32 v113, v113
	v_exp_f32_e32 v114, v114
	v_exp_f32_e32 v115, v115
	v_add_f32_e32 v112, 1.0, v112
	v_add_f32_e32 v113, 1.0, v113
	v_add_f32_e32 v114, 1.0, v114
	v_add_f32_e32 v115, 1.0, v115
	v_rcp_f32_e32 v112, v112
	v_rcp_f32_e32 v113, v113
	v_rcp_f32_e32 v114, v114
	v_rcp_f32_e32 v115, v115
	v_pk_mul_f32 v[104:105], v[104:105], v[112:113]
	v_pk_mul_f32 v[106:107], v[106:107], v[114:115]
.LBB0_437:
	v_mov_b32_e32 v178, v179
	v_mov_b32_e32 v116, v179
	v_mov_b32_e32 v117, v179
	v_mul_lo_u32 v113, s7, v176
	v_mul_lo_u32 v112, s6, v171
	v_mad_u64_u32 v[114:115], s[0:1], s6, v176, 0
	v_pk_mul_f32 v[102:103], v[102:103], v[116:117]
	v_pk_mul_f32 v[100:101], v[100:101], v[178:179]
	v_pk_mul_f32 v[98:99], v[98:99], v[116:117]
	v_pk_mul_f32 v[96:97], v[96:97], v[178:179]
	v_add3_u32 v115, v115, v112, v113
	v_pk_mul_f32 v[102:103], v[102:103], v[110:111]
	v_pk_mul_f32 v[100:101], v[100:101], v[108:109]
	v_pk_mul_f32 v[106:107], v[98:99], v[106:107]
	v_pk_mul_f32 v[98:99], v[96:97], v[104:105]
	v_lshl_add_u64 v[114:115], v[114:115], 1, v[138:139]
	v_cvt_pk_bf16_f32 v96, v100, v101
	v_cvt_pk_bf16_f32 v97, v102, v103
	v_cvt_pk_bf16_f32 v98, v98, v99
	v_cvt_pk_bf16_f32 v99, v106, v107
	v_pk_mul_f32 v[92:93], v[92:93], v[144:145] op_sel_hi:[1,0]
	v_pk_mul_f32 v[94:95], v[94:95], v[144:145] op_sel_hi:[1,0]
	v_pk_mul_f32 v[88:89], v[88:89], v[144:145] op_sel_hi:[1,0]
	s_and_b64 vcc, exec, s[42:43]
	v_pk_mul_f32 v[90:91], v[90:91], v[144:145] op_sel_hi:[1,0]
	global_store_dwordx4 v[114:115], v[96:99], off sc1
	s_cbranch_vccnz .LBB0_439
	s_nop 0
	v_mul_f32_e32 v96, 0xbfb8aa3b, v92
	v_mul_f32_e32 v97, 0xbfb8aa3b, v93
	v_mul_f32_e32 v98, 0xbfb8aa3b, v94
	v_mul_f32_e32 v99, 0xbfb8aa3b, v95
	v_exp_f32_e32 v96, v96
	v_exp_f32_e32 v97, v97
	v_exp_f32_e32 v98, v98
	v_exp_f32_e32 v99, v99
	v_add_f32_e32 v96, 1.0, v96
	v_add_f32_e32 v97, 1.0, v97
	v_add_f32_e32 v98, 1.0, v98
	v_add_f32_e32 v99, 1.0, v99
	v_rcp_f32_e32 v96, v96
	v_rcp_f32_e32 v97, v97
	v_rcp_f32_e32 v98, v98
	v_rcp_f32_e32 v99, v99
	v_pk_mul_f32 v[92:93], v[92:93], v[96:97]
	v_mul_f32_e32 v96, 0xbfb8aa3b, v88
	v_pk_mul_f32 v[94:95], v[94:95], v[98:99]
	v_mul_f32_e32 v97, 0xbfb8aa3b, v89
	v_mul_f32_e32 v98, 0xbfb8aa3b, v90
	v_mul_f32_e32 v99, 0xbfb8aa3b, v91
	v_exp_f32_e32 v96, v96
	v_exp_f32_e32 v97, v97
	v_exp_f32_e32 v98, v98
	v_exp_f32_e32 v99, v99
	v_add_f32_e32 v96, 1.0, v96
	v_add_f32_e32 v97, 1.0, v97
	v_add_f32_e32 v98, 1.0, v98
	v_add_f32_e32 v99, 1.0, v99
	v_rcp_f32_e32 v96, v96
	v_rcp_f32_e32 v97, v97
	v_rcp_f32_e32 v98, v98
	v_rcp_f32_e32 v99, v99
	v_pk_mul_f32 v[88:89], v[88:89], v[96:97]
	v_pk_mul_f32 v[90:91], v[90:91], v[98:99]
.LBB0_439:
	v_mul_lo_u32 v100, s7, v174
	v_mad_u64_u32 v[98:99], s[0:1], s6, v174, 0
	v_mov_b32_e32 v96, v144
	v_mov_b32_e32 v97, v144
	v_add3_u32 v99, v99, v112, v100
	v_mov_b32_e32 v100, v144
	v_mov_b32_e32 v101, v144
	v_pk_mul_f32 v[86:87], v[86:87], v[100:101]
	v_pk_mul_f32 v[84:85], v[84:85], v[96:97]
	v_pk_mul_f32 v[82:83], v[82:83], v[100:101]
	v_pk_mul_f32 v[80:81], v[80:81], v[96:97]
	v_pk_mul_f32 v[86:87], v[86:87], v[94:95]
	v_pk_mul_f32 v[84:85], v[84:85], v[92:93]
	v_pk_mul_f32 v[90:91], v[82:83], v[90:91]
	v_pk_mul_f32 v[82:83], v[80:81], v[88:89]
	v_lshl_add_u64 v[98:99], v[98:99], 1, v[138:139]
	v_cvt_pk_bf16_f32 v80, v84, v85
	v_cvt_pk_bf16_f32 v81, v86, v87
	v_cvt_pk_bf16_f32 v82, v82, v83
	v_cvt_pk_bf16_f32 v83, v90, v91
	v_pk_mul_f32 v[76:77], v[76:77], v[144:145] op_sel:[0,1]
	v_pk_mul_f32 v[78:79], v[78:79], v[144:145] op_sel:[0,1]
	v_pk_mul_f32 v[72:73], v[72:73], v[144:145] op_sel:[0,1]
	s_and_b64 vcc, exec, s[42:43]
	v_pk_mul_f32 v[74:75], v[74:75], v[144:145] op_sel:[0,1]
	global_store_dwordx4 v[98:99], v[80:83], off sc1
	s_cbranch_vccnz .LBB0_441
	s_nop 0
	v_mul_f32_e32 v80, 0xbfb8aa3b, v76
	v_mul_f32_e32 v81, 0xbfb8aa3b, v77
	v_mul_f32_e32 v82, 0xbfb8aa3b, v78
	v_mul_f32_e32 v83, 0xbfb8aa3b, v79
	v_exp_f32_e32 v80, v80
	v_exp_f32_e32 v81, v81
	v_exp_f32_e32 v82, v82
	v_exp_f32_e32 v83, v83
	v_add_f32_e32 v80, 1.0, v80
	v_add_f32_e32 v81, 1.0, v81
	v_add_f32_e32 v82, 1.0, v82
	v_add_f32_e32 v83, 1.0, v83
	v_rcp_f32_e32 v80, v80
	v_rcp_f32_e32 v81, v81
	v_rcp_f32_e32 v82, v82
	v_rcp_f32_e32 v83, v83
	v_pk_mul_f32 v[76:77], v[76:77], v[80:81]
	v_mul_f32_e32 v80, 0xbfb8aa3b, v72
	v_pk_mul_f32 v[78:79], v[78:79], v[82:83]
	v_mul_f32_e32 v81, 0xbfb8aa3b, v73
	v_mul_f32_e32 v82, 0xbfb8aa3b, v74
	v_mul_f32_e32 v83, 0xbfb8aa3b, v75
	v_exp_f32_e32 v80, v80
	v_exp_f32_e32 v81, v81
	v_exp_f32_e32 v82, v82
	v_exp_f32_e32 v83, v83
	v_add_f32_e32 v80, 1.0, v80
	v_add_f32_e32 v81, 1.0, v81
	v_add_f32_e32 v82, 1.0, v82
	v_add_f32_e32 v83, 1.0, v83
	v_rcp_f32_e32 v80, v80
	v_rcp_f32_e32 v81, v81
	v_rcp_f32_e32 v82, v82
	v_rcp_f32_e32 v83, v83
	v_pk_mul_f32 v[72:73], v[72:73], v[80:81]
	v_pk_mul_f32 v[74:75], v[74:75], v[82:83]
.LBB0_441:
	s_nop 0
	v_mul_lo_u32 v82, s7, v172
	v_mad_u64_u32 v[80:81], s[0:1], s6, v172, 0
	v_mov_b32_e32 v144, v145
	v_add3_u32 v81, v81, v112, v82
	v_mov_b32_e32 v82, v145
	v_mov_b32_e32 v83, v145
	v_pk_mul_f32 v[70:71], v[70:71], v[82:83]
	v_pk_mul_f32 v[68:69], v[68:69], v[144:145]
	v_pk_mul_f32 v[66:67], v[66:67], v[82:83]
	v_pk_mul_f32 v[64:65], v[64:65], v[144:145]
	v_pk_mul_f32 v[70:71], v[70:71], v[78:79]
	v_pk_mul_f32 v[68:69], v[68:69], v[76:77]
	v_pk_mul_f32 v[74:75], v[66:67], v[74:75]
	v_pk_mul_f32 v[66:67], v[64:65], v[72:73]
	v_lshl_add_u64 v[80:81], v[80:81], 1, v[138:139]
	v_cvt_pk_bf16_f32 v64, v68, v69
	v_cvt_pk_bf16_f32 v65, v70, v71
	v_cvt_pk_bf16_f32 v66, v66, v67
	v_cvt_pk_bf16_f32 v67, v74, v75
	v_pk_mul_f32 v[60:61], v[60:61], v[140:141] op_sel_hi:[1,0]
	v_pk_mul_f32 v[62:63], v[62:63], v[140:141] op_sel_hi:[1,0]
	v_pk_mul_f32 v[56:57], v[56:57], v[140:141] op_sel_hi:[1,0]
	s_and_b64 vcc, exec, s[42:43]
	v_pk_mul_f32 v[58:59], v[58:59], v[140:141] op_sel_hi:[1,0]
	global_store_dwordx4 v[80:81], v[64:67], off sc1
	s_cbranch_vccnz .LBB0_443
	s_nop 0
	v_mul_f32_e32 v64, 0xbfb8aa3b, v60
	v_mul_f32_e32 v65, 0xbfb8aa3b, v61
	v_mul_f32_e32 v66, 0xbfb8aa3b, v62
	v_mul_f32_e32 v67, 0xbfb8aa3b, v63
	v_exp_f32_e32 v64, v64
	v_exp_f32_e32 v65, v65
	v_exp_f32_e32 v66, v66
	v_exp_f32_e32 v67, v67
	v_add_f32_e32 v64, 1.0, v64
	v_add_f32_e32 v65, 1.0, v65
	v_add_f32_e32 v66, 1.0, v66
	v_add_f32_e32 v67, 1.0, v67
	v_rcp_f32_e32 v64, v64
	v_rcp_f32_e32 v65, v65
	v_rcp_f32_e32 v66, v66
	v_rcp_f32_e32 v67, v67
	v_pk_mul_f32 v[60:61], v[60:61], v[64:65]
	v_mul_f32_e32 v64, 0xbfb8aa3b, v56
	v_pk_mul_f32 v[62:63], v[62:63], v[66:67]
	v_mul_f32_e32 v65, 0xbfb8aa3b, v57
	v_mul_f32_e32 v66, 0xbfb8aa3b, v58
	v_mul_f32_e32 v67, 0xbfb8aa3b, v59
	v_exp_f32_e32 v64, v64
	v_exp_f32_e32 v65, v65
	v_exp_f32_e32 v66, v66
	v_exp_f32_e32 v67, v67
	v_add_f32_e32 v64, 1.0, v64
	v_add_f32_e32 v65, 1.0, v65
	v_add_f32_e32 v66, 1.0, v66
	v_add_f32_e32 v67, 1.0, v67
	v_rcp_f32_e32 v64, v64
	v_rcp_f32_e32 v65, v65
	v_rcp_f32_e32 v66, v66
	v_rcp_f32_e32 v67, v67
	v_pk_mul_f32 v[56:57], v[56:57], v[64:65]
	v_pk_mul_f32 v[58:59], v[58:59], v[66:67]
.LBB0_443:
	s_nop 0
	v_add_u32_e32 v66, 0x80, v170
	v_ashrrev_i32_e32 v67, 31, v66
	v_mul_lo_u32 v68, s6, v67
	v_mul_lo_u32 v69, s7, v66
	v_mad_u64_u32 v[66:67], s[0:1], s6, v66, 0
	v_mov_b32_e32 v64, v140
	v_mov_b32_e32 v65, v140
	v_add3_u32 v67, v67, v68, v69
	v_mov_b32_e32 v68, v140
	v_mov_b32_e32 v69, v140
	v_pk_mul_f32 v[54:55], v[54:55], v[68:69]
	v_pk_mul_f32 v[52:53], v[52:53], v[64:65]
	v_pk_mul_f32 v[50:51], v[50:51], v[68:69]
	v_pk_mul_f32 v[48:49], v[48:49], v[64:65]
	v_pk_mul_f32 v[54:55], v[54:55], v[62:63]
	v_pk_mul_f32 v[52:53], v[52:53], v[60:61]
	v_pk_mul_f32 v[58:59], v[50:51], v[58:59]
	v_pk_mul_f32 v[50:51], v[48:49], v[56:57]
	v_lshl_add_u64 v[66:67], v[66:67], 1, v[138:139]
	v_cvt_pk_bf16_f32 v48, v52, v53
	v_cvt_pk_bf16_f32 v49, v54, v55
	v_cvt_pk_bf16_f32 v50, v50, v51
	v_cvt_pk_bf16_f32 v51, v58, v59
	v_pk_mul_f32 v[44:45], v[44:45], v[140:141] op_sel:[0,1]
	v_pk_mul_f32 v[46:47], v[46:47], v[140:141] op_sel:[0,1]
	v_pk_mul_f32 v[40:41], v[40:41], v[140:141] op_sel:[0,1]
	s_and_b64 vcc, exec, s[42:43]
	v_pk_mul_f32 v[42:43], v[42:43], v[140:141] op_sel:[0,1]
	global_store_dwordx4 v[66:67], v[48:51], off sc1
	s_cbranch_vccnz .LBB0_445
	s_nop 0
	v_mul_f32_e32 v48, 0xbfb8aa3b, v44
	v_mul_f32_e32 v49, 0xbfb8aa3b, v45
	v_mul_f32_e32 v50, 0xbfb8aa3b, v46
	v_mul_f32_e32 v51, 0xbfb8aa3b, v47
	v_exp_f32_e32 v48, v48
	v_exp_f32_e32 v49, v49
	v_exp_f32_e32 v50, v50
	v_exp_f32_e32 v51, v51
	v_add_f32_e32 v48, 1.0, v48
	v_add_f32_e32 v49, 1.0, v49
	v_add_f32_e32 v50, 1.0, v50
	v_add_f32_e32 v51, 1.0, v51
	v_rcp_f32_e32 v48, v48
	v_rcp_f32_e32 v49, v49
	v_rcp_f32_e32 v50, v50
	v_rcp_f32_e32 v51, v51
	v_pk_mul_f32 v[44:45], v[44:45], v[48:49]
	v_mul_f32_e32 v48, 0xbfb8aa3b, v40
	v_pk_mul_f32 v[46:47], v[46:47], v[50:51]
	v_mul_f32_e32 v49, 0xbfb8aa3b, v41
	v_mul_f32_e32 v50, 0xbfb8aa3b, v42
	v_mul_f32_e32 v51, 0xbfb8aa3b, v43
	v_exp_f32_e32 v48, v48
	v_exp_f32_e32 v49, v49
	v_exp_f32_e32 v50, v50
	v_exp_f32_e32 v51, v51
	v_add_f32_e32 v48, 1.0, v48
	v_add_f32_e32 v49, 1.0, v49
	v_add_f32_e32 v50, 1.0, v50
	v_add_f32_e32 v51, 1.0, v51
	v_rcp_f32_e32 v48, v48
	v_rcp_f32_e32 v49, v49
	v_rcp_f32_e32 v50, v50
	v_rcp_f32_e32 v51, v51
	v_pk_mul_f32 v[40:41], v[40:41], v[48:49]
	v_pk_mul_f32 v[42:43], v[42:43], v[50:51]
.LBB0_445:
	s_nop 0
	v_add_u32_e32 v48, 0x90, v170
	v_ashrrev_i32_e32 v49, 31, v48
	v_mul_lo_u32 v50, s6, v49
	v_mul_lo_u32 v51, s7, v48
	v_mad_u64_u32 v[48:49], s[0:1], s6, v48, 0
	v_mov_b32_e32 v140, v141
	v_add3_u32 v49, v49, v50, v51
	v_mov_b32_e32 v50, v141
	v_mov_b32_e32 v51, v141
	v_pk_mul_f32 v[38:39], v[38:39], v[50:51]
	v_pk_mul_f32 v[36:37], v[36:37], v[140:141]
	v_pk_mul_f32 v[34:35], v[34:35], v[50:51]
	v_pk_mul_f32 v[32:33], v[32:33], v[140:141]
	v_pk_mul_f32 v[38:39], v[38:39], v[46:47]
	v_pk_mul_f32 v[36:37], v[36:37], v[44:45]
	v_pk_mul_f32 v[42:43], v[34:35], v[42:43]
	v_pk_mul_f32 v[34:35], v[32:33], v[40:41]
	v_lshl_add_u64 v[48:49], v[48:49], 1, v[138:139]
	v_cvt_pk_bf16_f32 v32, v36, v37
	v_cvt_pk_bf16_f32 v33, v38, v39
	v_cvt_pk_bf16_f32 v34, v34, v35
	v_cvt_pk_bf16_f32 v35, v42, v43
	v_pk_mul_f32 v[28:29], v[28:29], v[136:137] op_sel_hi:[1,0]
	v_pk_mul_f32 v[30:31], v[30:31], v[136:137] op_sel_hi:[1,0]
	v_pk_mul_f32 v[24:25], v[24:25], v[136:137] op_sel_hi:[1,0]
	s_and_b64 vcc, exec, s[42:43]
	v_pk_mul_f32 v[26:27], v[26:27], v[136:137] op_sel_hi:[1,0]
	global_store_dwordx4 v[48:49], v[32:35], off sc1
	s_cbranch_vccnz .LBB0_447
	s_nop 0
	v_mul_f32_e32 v32, 0xbfb8aa3b, v28
	v_mul_f32_e32 v33, 0xbfb8aa3b, v29
	v_mul_f32_e32 v34, 0xbfb8aa3b, v30
	v_mul_f32_e32 v35, 0xbfb8aa3b, v31
	v_exp_f32_e32 v32, v32
	v_exp_f32_e32 v33, v33
	v_exp_f32_e32 v34, v34
	v_exp_f32_e32 v35, v35
	v_add_f32_e32 v32, 1.0, v32
	v_add_f32_e32 v33, 1.0, v33
	v_add_f32_e32 v34, 1.0, v34
	v_add_f32_e32 v35, 1.0, v35
	v_rcp_f32_e32 v32, v32
	v_rcp_f32_e32 v33, v33
	v_rcp_f32_e32 v34, v34
	v_rcp_f32_e32 v35, v35
	v_pk_mul_f32 v[28:29], v[28:29], v[32:33]
	v_mul_f32_e32 v32, 0xbfb8aa3b, v24
	v_pk_mul_f32 v[30:31], v[30:31], v[34:35]
	v_mul_f32_e32 v33, 0xbfb8aa3b, v25
	v_mul_f32_e32 v34, 0xbfb8aa3b, v26
	v_mul_f32_e32 v35, 0xbfb8aa3b, v27
	v_exp_f32_e32 v32, v32
	v_exp_f32_e32 v33, v33
	v_exp_f32_e32 v34, v34
	v_exp_f32_e32 v35, v35
	v_add_f32_e32 v32, 1.0, v32
	v_add_f32_e32 v33, 1.0, v33
	v_add_f32_e32 v34, 1.0, v34
	v_add_f32_e32 v35, 1.0, v35
	v_rcp_f32_e32 v32, v32
	v_rcp_f32_e32 v33, v33
	v_rcp_f32_e32 v34, v34
	v_rcp_f32_e32 v35, v35
	v_pk_mul_f32 v[24:25], v[24:25], v[32:33]
	v_pk_mul_f32 v[26:27], v[26:27], v[34:35]
.LBB0_447:
	s_nop 0
	v_add_u32_e32 v34, 0xa0, v170
	v_ashrrev_i32_e32 v35, 31, v34
	v_mul_lo_u32 v36, s6, v35
	v_mul_lo_u32 v37, s7, v34
	v_mad_u64_u32 v[34:35], s[0:1], s6, v34, 0
	v_mov_b32_e32 v32, v136
	v_mov_b32_e32 v33, v136
	v_add3_u32 v35, v35, v36, v37
	v_mov_b32_e32 v36, v136
	v_mov_b32_e32 v37, v136
	v_pk_mul_f32 v[22:23], v[22:23], v[36:37]
	v_pk_mul_f32 v[20:21], v[20:21], v[32:33]
	v_pk_mul_f32 v[18:19], v[18:19], v[36:37]
	v_pk_mul_f32 v[16:17], v[16:17], v[32:33]
	v_pk_mul_f32 v[22:23], v[22:23], v[30:31]
	v_pk_mul_f32 v[20:21], v[20:21], v[28:29]
	v_pk_mul_f32 v[26:27], v[18:19], v[26:27]
	v_pk_mul_f32 v[18:19], v[16:17], v[24:25]
	v_lshl_add_u64 v[34:35], v[34:35], 1, v[138:139]
	v_cvt_pk_bf16_f32 v16, v20, v21
	v_cvt_pk_bf16_f32 v17, v22, v23
	v_cvt_pk_bf16_f32 v18, v18, v19
	v_cvt_pk_bf16_f32 v19, v26, v27
	v_pk_mul_f32 v[12:13], v[12:13], v[136:137] op_sel:[0,1]
	v_pk_mul_f32 v[14:15], v[14:15], v[136:137] op_sel:[0,1]
	v_pk_mul_f32 v[8:9], v[8:9], v[136:137] op_sel:[0,1]
	s_and_b64 vcc, exec, s[42:43]
	v_pk_mul_f32 v[10:11], v[10:11], v[136:137] op_sel:[0,1]
	global_store_dwordx4 v[34:35], v[16:19], off sc1
	s_cbranch_vccnz .LBB0_449
	s_nop 0
	v_mul_f32_e32 v16, 0xbfb8aa3b, v12
	v_mul_f32_e32 v17, 0xbfb8aa3b, v13
	v_mul_f32_e32 v18, 0xbfb8aa3b, v14
	v_mul_f32_e32 v19, 0xbfb8aa3b, v15
	v_exp_f32_e32 v16, v16
	v_exp_f32_e32 v17, v17
	v_exp_f32_e32 v18, v18
	v_exp_f32_e32 v19, v19
	v_add_f32_e32 v16, 1.0, v16
	v_add_f32_e32 v17, 1.0, v17
	v_add_f32_e32 v18, 1.0, v18
	v_add_f32_e32 v19, 1.0, v19
	v_rcp_f32_e32 v16, v16
	v_rcp_f32_e32 v17, v17
	v_rcp_f32_e32 v18, v18
	v_rcp_f32_e32 v19, v19
	v_pk_mul_f32 v[12:13], v[12:13], v[16:17]
	v_mul_f32_e32 v16, 0xbfb8aa3b, v8
	v_pk_mul_f32 v[14:15], v[14:15], v[18:19]
	v_mul_f32_e32 v17, 0xbfb8aa3b, v9
	v_mul_f32_e32 v18, 0xbfb8aa3b, v10
	v_mul_f32_e32 v19, 0xbfb8aa3b, v11
	v_exp_f32_e32 v16, v16
	v_exp_f32_e32 v17, v17
	v_exp_f32_e32 v18, v18
	v_exp_f32_e32 v19, v19
	v_add_f32_e32 v16, 1.0, v16
	v_add_f32_e32 v17, 1.0, v17
	v_add_f32_e32 v18, 1.0, v18
	v_add_f32_e32 v19, 1.0, v19
	v_rcp_f32_e32 v16, v16
	v_rcp_f32_e32 v17, v17
	v_rcp_f32_e32 v18, v18
	v_rcp_f32_e32 v19, v19
	v_pk_mul_f32 v[8:9], v[8:9], v[16:17]
	v_pk_mul_f32 v[10:11], v[10:11], v[18:19]
.LBB0_449:
	s_nop 0
	v_add_u32_e32 v16, 0xb0, v170
	v_ashrrev_i32_e32 v17, 31, v16
	v_mul_lo_u32 v18, s6, v17
	v_mul_lo_u32 v19, s7, v16
	v_mad_u64_u32 v[16:17], s[0:1], s6, v16, 0
	v_mov_b32_e32 v136, v137
	v_add3_u32 v17, v17, v18, v19
	v_mov_b32_e32 v18, v137
	v_mov_b32_e32 v19, v137
	v_pk_mul_f32 v[6:7], v[6:7], v[18:19]
	v_pk_mul_f32 v[4:5], v[4:5], v[136:137]
	v_pk_mul_f32 v[2:3], v[2:3], v[18:19]
	v_pk_mul_f32 v[0:1], v[0:1], v[136:137]
	v_pk_mul_f32 v[6:7], v[6:7], v[14:15]
	v_pk_mul_f32 v[4:5], v[4:5], v[12:13]
	v_pk_mul_f32 v[10:11], v[2:3], v[10:11]
	v_pk_mul_f32 v[2:3], v[0:1], v[8:9]
	v_lshl_add_u64 v[16:17], v[16:17], 1, v[138:139]
	v_cvt_pk_bf16_f32 v0, v4, v5
	v_cvt_pk_bf16_f32 v1, v6, v7
	v_cvt_pk_bf16_f32 v2, v2, v3
	v_cvt_pk_bf16_f32 v3, v10, v11
	global_store_dwordx4 v[16:17], v[0:3], off sc1
	s_and_b64 vcc, exec, s[40:41]
	s_mov_b64 s[0:1], -1
	s_cbranch_vccnz .LBB0_360

.LBB0_620:
	s_andn2_saveexec_b64 s[2:3], s[4:5]
	s_cbranch_execz .LBB0_640
	s_mov_b64 s[4:5], exec
	s_bitcmp1_b32 0x124a8, s86
	s_cbranch_scc1 .Lseam_nowb
	buffer_wbl2 sc1
.Lseam_nowb:
	s_waitcnt lgkmcnt(0)
	s_waitcnt vmcnt(0)
	v_mbcnt_lo_u32_b32 v1, s4, 0
	v_mbcnt_hi_u32_b32 v1, s5, v1
	v_cmp_eq_u32_e32 vcc, 0, v1
	s_and_saveexec_b64 s[6:7], vcc
	s_cbranch_execz .LBB0_623
	s_bcnt1_i32_b64 s2, s[4:5]
	v_mov_b32_e32 v2, s2
	v_readlane_b32 s2, v246, 53
	v_readlane_b32 s3, v246, 54
	s_nop 4
	global_atomic_add v2, v155, v2, s[2:3] sc0
